# v54 + de-serialized G3 epilogue (all operand loads issued first)
# speedup vs baseline: 1.0540x; 1.0062x over previous
.LBB1_82:
	s_lshl_b32 s19, s18, 8
	s_add_i32 s19, s19, 0x80
	s_min_u32 s19, s19, 0x780
	s_add_u32 s40, s8, s19
	s_addc_u32 s41, s9, 0
	s_add_u32 s42, s10, s19
	s_addc_u32 s43, s11, 0
	ds_read_b128 v[142:145], v234 offset:0
	ds_read_b128 v[146:149], v234 offset:2048
	ds_read_b128 v[150:153], v234 offset:4096
	ds_read_b128 v[154:157], v234 offset:6144
	ds_read_b128 v[130:133], v232 offset:0
	ds_read_b128 v[134:137], v232 offset:2048
	ds_read_b128 v[138:141], v232 offset:4096
	ds_read_b128 v[216:219], v235 offset:0
	ds_read_b128 v[220:223], v235 offset:2048
	ds_read_b128 v[224:227], v235 offset:4096
	ds_read_b128 v[228:231], v235 offset:6144
	ds_read_b128 v[188:191], v233 offset:0
	ds_read_b128 v[192:195], v233 offset:2048
	ds_read_b128 v[196:199], v233 offset:4096
	s_waitcnt lgkmcnt(9)
	s_add_i32 m0, s16, 0x7010
	s_nop 0
	v_mfma_f32_16x16x32_bf16 v[72:75], v[142:145], v[130:133], v[72:75]
	global_load_lds_dwordx4 v238, s[40:41]
	s_add_i32 m0, s16, 0x7410
	s_add_u32 s12, s40, 0x4000
	s_addc_u32 s13, s41, 0
	v_mfma_f32_16x16x32_bf16 v[68:71], v[146:149], v[130:133], v[68:71]
	global_load_lds_dwordx4 v239, s[12:13]
	v_mfma_f32_16x16x32_bf16 v[44:47], v[150:153], v[130:133], v[44:47]
	v_mfma_f32_16x16x32_bf16 v[32:35], v[154:157], v[130:133], v[32:35]
	s_waitcnt lgkmcnt(8)
	s_add_i32 m0, s16, 0x7810
	s_add_u32 s12, s40, 0x8000
	s_addc_u32 s13, s41, 0
	v_mfma_f32_16x16x32_bf16 v[28:31], v[142:145], v[134:137], v[28:31]
	v_mfma_f32_16x16x32_bf16 v[24:27], v[146:149], v[134:137], v[24:27]
	global_load_lds_dwordx4 v238, s[12:13]
	v_mfma_f32_16x16x32_bf16 v[20:23], v[150:153], v[134:137], v[20:23]
	v_mfma_f32_16x16x32_bf16 v[16:19], v[154:157], v[134:137], v[16:19]
	s_waitcnt lgkmcnt(7)
	s_add_i32 m0, s17, 0xa010
	s_nop 0
	v_mfma_f32_16x16x32_bf16 v[12:15], v[142:145], v[138:141], v[12:15]
	v_mfma_f32_16x16x32_bf16 v[8:11], v[146:149], v[138:141], v[8:11]
	global_load_lds_dwordx4 v236, s[42:43]
	v_mfma_f32_16x16x32_bf16 v[4:7], v[150:153], v[138:141], v[4:7]
	v_mfma_f32_16x16x32_bf16 v[0:3], v[154:157], v[138:141], v[0:3]
	s_waitcnt lgkmcnt(2)
	s_add_i32 m0, s17, 0xa410
	s_add_u32 s12, s42, 0x4000
	s_addc_u32 s13, s43, 0
	v_mfma_f32_16x16x32_bf16 v[72:75], v[216:219], v[188:191], v[72:75]
	v_mfma_f32_16x16x32_bf16 v[68:71], v[220:223], v[188:191], v[68:71]
	global_load_lds_dwordx4 v237, s[12:13]
	v_mfma_f32_16x16x32_bf16 v[44:47], v[224:227], v[188:191], v[44:47]
	v_mfma_f32_16x16x32_bf16 v[32:35], v[228:231], v[188:191], v[32:35]
	s_waitcnt lgkmcnt(1)
	s_add_i32 m0, s17, 0xa810
	s_add_u32 s12, s42, 0x8000
	s_addc_u32 s13, s43, 0
	v_mfma_f32_16x16x32_bf16 v[28:31], v[216:219], v[192:195], v[28:31]
	v_mfma_f32_16x16x32_bf16 v[24:27], v[220:223], v[192:195], v[24:27]
	global_load_lds_dwordx4 v236, s[12:13]
	v_mfma_f32_16x16x32_bf16 v[20:23], v[224:227], v[192:195], v[20:23]
	v_mfma_f32_16x16x32_bf16 v[16:19], v[228:231], v[192:195], v[16:19]
	s_waitcnt lgkmcnt(0)
	s_add_i32 m0, s17, 0xac10
	s_add_u32 s12, s42, 0xc000
	s_addc_u32 s13, s43, 0
	v_mfma_f32_16x16x32_bf16 v[12:15], v[216:219], v[196:199], v[12:15]
	v_mfma_f32_16x16x32_bf16 v[8:11], v[220:223], v[196:199], v[8:11]
	global_load_lds_dwordx4 v237, s[12:13]
	v_mfma_f32_16x16x32_bf16 v[4:7], v[224:227], v[196:199], v[4:7]
	v_mfma_f32_16x16x32_bf16 v[0:3], v[228:231], v[196:199], v[0:3]
	s_waitcnt vmcnt(0)
	s_barrier
	s_lshl_b32 s19, s18, 8
	s_add_i32 s19, s19, 0x100
	s_min_u32 s19, s19, 0x780
	s_add_u32 s40, s8, s19
	s_addc_u32 s41, s9, 0
	s_add_u32 s42, s10, s19
	s_addc_u32 s43, s11, 0
	ds_read_b128 v[142:145], v234 offset:28672
	ds_read_b128 v[146:149], v234 offset:30720
	ds_read_b128 v[150:153], v234 offset:32768
	ds_read_b128 v[154:157], v234 offset:34816
	ds_read_b128 v[130:133], v232 offset:28672
	ds_read_b128 v[134:137], v232 offset:30720
	ds_read_b128 v[138:141], v232 offset:32768
	ds_read_b128 v[216:219], v235 offset:28672
	ds_read_b128 v[220:223], v235 offset:30720
	ds_read_b128 v[224:227], v235 offset:32768
	ds_read_b128 v[228:231], v235 offset:34816
	ds_read_b128 v[188:191], v233 offset:28672
	ds_read_b128 v[192:195], v233 offset:30720
	ds_read_b128 v[196:199], v233 offset:32768
	s_waitcnt lgkmcnt(9)
	s_add_i32 m0, s16, 0x10
	s_nop 0
	v_mfma_f32_16x16x32_bf16 v[72:75], v[142:145], v[130:133], v[72:75]
	global_load_lds_dwordx4 v238, s[40:41]
	s_add_i32 m0, s16, 0x410
	s_add_u32 s12, s40, 0x4000
	s_addc_u32 s13, s41, 0
	v_mfma_f32_16x16x32_bf16 v[68:71], v[146:149], v[130:133], v[68:71]
	global_load_lds_dwordx4 v239, s[12:13]
	v_mfma_f32_16x16x32_bf16 v[44:47], v[150:153], v[130:133], v[44:47]
	v_mfma_f32_16x16x32_bf16 v[32:35], v[154:157], v[130:133], v[32:35]
	s_waitcnt lgkmcnt(8)
	s_add_i32 m0, s16, 0x810
	s_add_u32 s12, s40, 0x8000
	s_addc_u32 s13, s41, 0
	v_mfma_f32_16x16x32_bf16 v[28:31], v[142:145], v[134:137], v[28:31]
	v_mfma_f32_16x16x32_bf16 v[24:27], v[146:149], v[134:137], v[24:27]
	global_load_lds_dwordx4 v238, s[12:13]
	v_mfma_f32_16x16x32_bf16 v[20:23], v[150:153], v[134:137], v[20:23]
	v_mfma_f32_16x16x32_bf16 v[16:19], v[154:157], v[134:137], v[16:19]
	s_waitcnt lgkmcnt(7)
	s_add_i32 m0, s17, 0x3010
	s_nop 0
	v_mfma_f32_16x16x32_bf16 v[12:15], v[142:145], v[138:141], v[12:15]
	v_mfma_f32_16x16x32_bf16 v[8:11], v[146:149], v[138:141], v[8:11]
	global_load_lds_dwordx4 v236, s[42:43]
	v_mfma_f32_16x16x32_bf16 v[4:7], v[150:153], v[138:141], v[4:7]
	v_mfma_f32_16x16x32_bf16 v[0:3], v[154:157], v[138:141], v[0:3]
	s_waitcnt lgkmcnt(2)
	s_add_i32 m0, s17, 0x3410
	s_add_u32 s12, s42, 0x4000
	s_addc_u32 s13, s43, 0
	v_mfma_f32_16x16x32_bf16 v[72:75], v[216:219], v[188:191], v[72:75]
	v_mfma_f32_16x16x32_bf16 v[68:71], v[220:223], v[188:191], v[68:71]
	global_load_lds_dwordx4 v237, s[12:13]
	v_mfma_f32_16x16x32_bf16 v[44:47], v[224:227], v[188:191], v[44:47]
	v_mfma_f32_16x16x32_bf16 v[32:35], v[228:231], v[188:191], v[32:35]
	s_waitcnt lgkmcnt(1)
	s_add_i32 m0, s17, 0x3810
	s_add_u32 s12, s42, 0x8000
	s_addc_u32 s13, s43, 0
	v_mfma_f32_16x16x32_bf16 v[28:31], v[216:219], v[192:195], v[28:31]
	v_mfma_f32_16x16x32_bf16 v[24:27], v[220:223], v[192:195], v[24:27]
	global_load_lds_dwordx4 v236, s[12:13]
	v_mfma_f32_16x16x32_bf16 v[20:23], v[224:227], v[192:195], v[20:23]
	v_mfma_f32_16x16x32_bf16 v[16:19], v[228:231], v[192:195], v[16:19]
	s_waitcnt lgkmcnt(0)
	s_add_i32 m0, s17, 0x3c10
	s_add_u32 s12, s42, 0xc000
	s_addc_u32 s13, s43, 0
	v_mfma_f32_16x16x32_bf16 v[12:15], v[216:219], v[196:199], v[12:15]
	v_mfma_f32_16x16x32_bf16 v[8:11], v[220:223], v[196:199], v[8:11]
	global_load_lds_dwordx4 v237, s[12:13]
	v_mfma_f32_16x16x32_bf16 v[4:7], v[224:227], v[196:199], v[4:7]
	v_mfma_f32_16x16x32_bf16 v[0:3], v[228:231], v[196:199], v[0:3]
	s_waitcnt vmcnt(0)
	s_barrier
	s_add_i32 s18, s18, 1
	s_cmp_eq_u32 s18, 8
	s_cbranch_scc0 .LBB1_82
	s_setprio 0
	s_waitcnt vmcnt(0)
	v_readlane_b32 s10, v241, 32
	v_readlane_b32 s11, v241, 33
	v_and_b32_e32 v36, 15, v162
	v_bfe_u32 v37, v162, 4, 2
	v_lshrrev_b32_e32 v38, 7, v162
	v_and_b32_e32 v39, 64, v162
	v_mul_u32_u24_e32 v38, 48, v38
	v_add3_u32 v40, v38, v36, s5
	v_lshl_or_b32 v41, v37, 2, v39
	v_add_u32_e32 v41, s4, v41
	v_lshlrev_b32_e32 v41, 2, v41
	s_movk_i32 s8, 0x1fff
	s_movk_i32 s9, 0x3fff
	s_add_u32 s10, s10, 0x2000
	s_addc_u32 s11, s11, 0
	s_mov_b32 s6, 0x3fd744fd
	v_mov_b32_e32 v42, v40
	v_cmp_lt_u32_e32 vcc, s9, v42
	v_lshl_add_u32 v64, v42, 12, v41
	s_nop 0
	v_cndmask_b32_e32 v43, v177, v176, vcc
	v_cmp_lt_u32_e32 vcc, s8, v42
	s_nop 1
	v_cndmask_b32_e32 v43, 0, v43, vcc
	v_lshl_add_u32 v124, v43, 2, v41
	v_add_u32_e32 v42, 16, v40
	v_cmp_lt_u32_e32 vcc, s9, v42
	v_lshl_add_u32 v65, v42, 12, v41
	s_nop 0
	v_cndmask_b32_e32 v43, v177, v176, vcc
	v_cmp_lt_u32_e32 vcc, s8, v42
	s_nop 1
	v_cndmask_b32_e32 v43, 0, v43, vcc
	v_lshl_add_u32 v125, v43, 2, v41
	v_add_u32_e32 v42, 32, v40
	v_cmp_lt_u32_e32 vcc, s9, v42
	v_lshl_add_u32 v66, v42, 12, v41
	s_nop 0
	v_cndmask_b32_e32 v43, v177, v176, vcc
	v_cmp_lt_u32_e32 vcc, s8, v42
	s_nop 1
	v_cndmask_b32_e32 v43, 0, v43, vcc
	v_lshl_add_u32 v126, v43, 2, v41
	global_load_dwordx4 v[130:133], v124, s[10:11] offset:0
	global_load_dwordx4 v[76:79], v64, s[70:71] offset:0
	global_load_dwordx4 v[134:137], v124, s[10:11] offset:64
	global_load_dwordx4 v[80:83], v64, s[70:71] offset:64
	global_load_dwordx4 v[138:141], v124, s[10:11] offset:128
	global_load_dwordx4 v[84:87], v64, s[70:71] offset:128
	global_load_dwordx4 v[142:145], v124, s[10:11] offset:192
	global_load_dwordx4 v[88:91], v64, s[70:71] offset:192
	global_load_dwordx4 v[146:149], v125, s[10:11] offset:0
	global_load_dwordx4 v[92:95], v65, s[70:71] offset:0
	global_load_dwordx4 v[150:153], v125, s[10:11] offset:64
	global_load_dwordx4 v[96:99], v65, s[70:71] offset:64
	global_load_dwordx4 v[154:157], v125, s[10:11] offset:128
	global_load_dwordx4 v[100:103], v65, s[70:71] offset:128
	global_load_dwordx4 v[158:161], v125, s[10:11] offset:192
	global_load_dwordx4 v[104:107], v65, s[70:71] offset:192
	global_load_dwordx4 v[48:51], v126, s[10:11] offset:0
	global_load_dwordx4 v[108:111], v66, s[70:71] offset:0
	global_load_dwordx4 v[52:55], v126, s[10:11] offset:64
	global_load_dwordx4 v[112:115], v66, s[70:71] offset:64
	global_load_dwordx4 v[56:59], v126, s[10:11] offset:128
	global_load_dwordx4 v[116:119], v66, s[70:71] offset:128
	global_load_dwordx4 v[60:63], v126, s[10:11] offset:192
	global_load_dwordx4 v[120:123], v66, s[70:71] offset:192
	s_add_i32 s2, s2, 1
	v_readlane_b32 s55, v241, 23
	s_waitcnt vmcnt(22)
	v_pk_mul_f32 v[130:131], v[72:73], v[130:131]
	v_pk_mul_f32 v[132:133], v[74:75], v[132:133]
	v_pk_fma_f32 v[76:77], v[76:77], s[6:7], v[130:131] op_sel_hi:[1,0,1]
	v_pk_fma_f32 v[78:79], v[78:79], s[6:7], v[132:133] op_sel_hi:[1,0,1]
	global_store_dwordx4 v64, v[76:79], s[72:73] offset:0
	s_waitcnt vmcnt(20)
	v_pk_mul_f32 v[134:135], v[68:69], v[134:135]
	v_pk_mul_f32 v[136:137], v[70:71], v[136:137]
	v_pk_fma_f32 v[80:81], v[80:81], s[6:7], v[134:135] op_sel_hi:[1,0,1]
	v_pk_fma_f32 v[82:83], v[82:83], s[6:7], v[136:137] op_sel_hi:[1,0,1]
	global_store_dwordx4 v64, v[80:83], s[72:73] offset:64
	s_waitcnt vmcnt(18)
	v_pk_mul_f32 v[138:139], v[44:45], v[138:139]
	v_pk_mul_f32 v[140:141], v[46:47], v[140:141]
	v_pk_fma_f32 v[84:85], v[84:85], s[6:7], v[138:139] op_sel_hi:[1,0,1]
	v_pk_fma_f32 v[86:87], v[86:87], s[6:7], v[140:141] op_sel_hi:[1,0,1]
	global_store_dwordx4 v64, v[84:87], s[72:73] offset:128
	s_waitcnt vmcnt(16)
	v_pk_mul_f32 v[142:143], v[32:33], v[142:143]
	v_pk_mul_f32 v[144:145], v[34:35], v[144:145]
	v_pk_fma_f32 v[88:89], v[88:89], s[6:7], v[142:143] op_sel_hi:[1,0,1]
	v_pk_fma_f32 v[90:91], v[90:91], s[6:7], v[144:145] op_sel_hi:[1,0,1]
	global_store_dwordx4 v64, v[88:91], s[72:73] offset:192
	s_waitcnt vmcnt(14)
	v_pk_mul_f32 v[146:147], v[28:29], v[146:147]
	v_pk_mul_f32 v[148:149], v[30:31], v[148:149]
	v_pk_fma_f32 v[92:93], v[92:93], s[6:7], v[146:147] op_sel_hi:[1,0,1]
	v_pk_fma_f32 v[94:95], v[94:95], s[6:7], v[148:149] op_sel_hi:[1,0,1]
	global_store_dwordx4 v65, v[92:95], s[72:73] offset:0
	s_waitcnt vmcnt(12)
	v_pk_mul_f32 v[150:151], v[24:25], v[150:151]
	v_pk_mul_f32 v[152:153], v[26:27], v[152:153]
	v_pk_fma_f32 v[96:97], v[96:97], s[6:7], v[150:151] op_sel_hi:[1,0,1]
	v_pk_fma_f32 v[98:99], v[98:99], s[6:7], v[152:153] op_sel_hi:[1,0,1]
	global_store_dwordx4 v65, v[96:99], s[72:73] offset:64
	s_waitcnt vmcnt(10)
	v_pk_mul_f32 v[154:155], v[20:21], v[154:155]
	v_pk_mul_f32 v[156:157], v[22:23], v[156:157]
	v_pk_fma_f32 v[100:101], v[100:101], s[6:7], v[154:155] op_sel_hi:[1,0,1]
	v_pk_fma_f32 v[102:103], v[102:103], s[6:7], v[156:157] op_sel_hi:[1,0,1]
	global_store_dwordx4 v65, v[100:103], s[72:73] offset:128
	s_waitcnt vmcnt(8)
	v_pk_mul_f32 v[158:159], v[16:17], v[158:159]
	v_pk_mul_f32 v[160:161], v[18:19], v[160:161]
	v_pk_fma_f32 v[104:105], v[104:105], s[6:7], v[158:159] op_sel_hi:[1,0,1]
	v_pk_fma_f32 v[106:107], v[106:107], s[6:7], v[160:161] op_sel_hi:[1,0,1]
	global_store_dwordx4 v65, v[104:107], s[72:73] offset:192
	s_waitcnt vmcnt(6)
	v_pk_mul_f32 v[48:49], v[12:13], v[48:49]
	v_pk_mul_f32 v[50:51], v[14:15], v[50:51]
	v_pk_fma_f32 v[108:109], v[108:109], s[6:7], v[48:49] op_sel_hi:[1,0,1]
	v_pk_fma_f32 v[110:111], v[110:111], s[6:7], v[50:51] op_sel_hi:[1,0,1]
	global_store_dwordx4 v66, v[108:111], s[72:73] offset:0
	s_waitcnt vmcnt(4)
	v_pk_mul_f32 v[52:53], v[8:9], v[52:53]
	v_pk_mul_f32 v[54:55], v[10:11], v[54:55]
	v_pk_fma_f32 v[112:113], v[112:113], s[6:7], v[52:53] op_sel_hi:[1,0,1]
	v_pk_fma_f32 v[114:115], v[114:115], s[6:7], v[54:55] op_sel_hi:[1,0,1]
	global_store_dwordx4 v66, v[112:115], s[72:73] offset:64
	s_waitcnt vmcnt(2)
	v_pk_mul_f32 v[56:57], v[4:5], v[56:57]
	v_pk_mul_f32 v[58:59], v[6:7], v[58:59]
	v_pk_fma_f32 v[116:117], v[116:117], s[6:7], v[56:57] op_sel_hi:[1,0,1]
	v_pk_fma_f32 v[118:119], v[118:119], s[6:7], v[58:59] op_sel_hi:[1,0,1]
	global_store_dwordx4 v66, v[116:119], s[72:73] offset:128
	s_waitcnt vmcnt(0)
	v_pk_mul_f32 v[60:61], v[0:1], v[60:61]
	v_pk_mul_f32 v[62:63], v[2:3], v[62:63]
	v_pk_fma_f32 v[120:121], v[120:121], s[6:7], v[60:61] op_sel_hi:[1,0,1]
	v_pk_fma_f32 v[122:123], v[122:123], s[6:7], v[62:63] op_sel_hi:[1,0,1]
	global_store_dwordx4 v66, v[120:123], s[72:73] offset:192
	s_mov_b64 s[30:31], 0
	s_branch .LBB1_79
